# barrier: no L2 write-back after phases whose only stores are the write-through GEMM epilogues (previous phase id read from the phase table)
# baseline (speedup 1.0000x reference)
; #define LAS __attribute__((address_space(3)))
; __global__ void __launch_bounds__(NTHR, 2) mega(P p, int ph_lo, int ph_hi) {
;     ...
;   for (int si = ph_lo; si < ph_hi; ++si) {
;     const int ph = p.seq[si];
;     if (si > ph_lo) { if (si == ph_lo + 1) { grid.sync(); xb = xcd_barrier_post(p.bar, (volatile LAS unsigned*)&xb_words); } else xcd_barrier(xb); }
.LBB0_14:
	s_ashr_i32 s4, s59, 31
	s_add_u32 s6, s0, s59
	s_addc_u32 s7, s1, s4
	global_load_ubyte v0, v135, s[6:7] offset:2128
	global_load_ubyte v1, v135, s[6:7] offset:2127
	s_cmp_le_i32 s59, s8
	s_waitcnt vmcnt(0)
	v_readfirstlane_b32 s60, v0
	v_readfirstlane_b32 s4, v1
	s_nop 0
	v_writelane_b32 v229, s4, 61
	s_cbranch_scc1 .LBB0_80
	v_readlane_b32 s4, v230, 5
	s_cmp_lg_u32 s59, s4
	s_mov_b64 s[6:7], -1
	s_cbranch_scc1 .Lxb_hr
	s_getreg_b32 s4, hwreg(HW_REG_XCC_ID, 0, 4)
	s_and_b32 s4, s4, 15
	s_nop 0
	v_writelane_b32 v229, s4, 26
	s_mov_b64 s[6:7], exec
	v_readlane_b32 s8, v230, 3
	v_readlane_b32 s9, v230, 4
	s_nop 3
	s_and_b64 s[8:9], s[6:7], s[8:9]
	s_mov_b64 exec, s[8:9]
	s_cbranch_execz .Lxb_fdone
	s_mov_b32 s10, 0

; __device__ __forceinline__ unsigned xb_add(unsigned* p, unsigned v) { return __hip_atomic_fetch_add(p, v, __ATOMIC_RELAXED, __HIP_MEMORY_SCOPE_AGENT); }
; __device__ __forceinline__ void xcd_barrier(const XcdBarrier& b) {
;     ...
;     if (old + 1u == (gen + 1u) * nloc) {
;       __builtin_amdgcn_fence(__ATOMIC_RELEASE, "agent");
;       asm volatile("s_waitcnt vmcnt(0)" ::: "memory");
;       const unsigned og = xb_add(&bar[XB_TOP], 1u);
;       const unsigned tg = og / nx;
;       if (og + 1u == (tg + 1u) * nx) xb_add(&bar[XB_TOPGEN], 1u);
.LBB0_46:
	s_andn2_saveexec_b64 s[10:11], s[10:11]
	s_cbranch_execz .LBB0_64
	v_mov_b32_e32 v5, v1
	v_sub_u32_e32 v6, v2, v1
	v_add_u32_e32 v6, -1, v6
	s_mov_b64 s[10:11], exec
	v_readlane_b32 s4, v229, 61
	s_nop 3
	s_lshr_b32 s4, 0x6a83540, s4
	s_and_b32 s4, s4, 1
	s_cmp_lg_u32 s4, 0
	s_cbranch_scc1 .Lxb_nowb
	buffer_wbl2 sc1
.Lxb_nowb:
	s_nop 0
	s_nop 0
	global_load_dword v7, v198, s[8:9] offset:1152 sc1
	s_waitcnt lgkmcnt(0)
	s_waitcnt vmcnt(0)
	s_mov_b32 s4, 0
	v_cmp_eq_u32_e32 vcc, v7, v6
	s_nop 1
	s_cbranch_vccnz .Lxb_idone
